# code placement: QG and WO GEMM K-loops shifted by 4 bytes so their 8-byte instructions (MFMA, ds_read) sit on 8-byte boundaries like the other K-loops
# baseline (speedup 1.0000x reference)
.LBB0_438:
	s_ashr_i32 s19, s18, 31
	s_lshl_b64 s[20:21], s[18:19], 19
	s_add_u32 s20, s37, s20
	s_addc_u32 s21, s38, s21
	s_and_b64 s[22:23], s[6:7], exec
	s_cselect_b32 s19, s21, s29
	s_cselect_b32 s25, s20, s28
	s_ashr_i32 s11, s10, 31
	s_lshl_b64 s[22:23], s[10:11], 19
	s_add_u32 s22, s39, s22
	s_addc_u32 s23, s40, s23
	s_and_b64 s[34:35], s[6:7], exec
	s_cselect_b32 s11, s23, s31
	s_cselect_b32 s27, s22, s30
	s_add_u32 s28, s28, 0x40080
	s_addc_u32 s29, s29, 0
	s_add_u32 s53, s30, 0x100
	v_mov_b32_e32 v4, 0
	s_addc_u32 s54, s31, 0
	s_mov_b32 s55, -2
	v_mov_b32_e32 v5, v4
	v_mov_b32_e32 v6, v4
	v_mov_b32_e32 v7, v4
	v_mov_b32_e32 v8, v4
	v_mov_b32_e32 v9, v4
	v_mov_b32_e32 v10, v4
	v_mov_b32_e32 v11, v4
	v_mov_b32_e32 v36, v4
	v_mov_b32_e32 v37, v4
	v_mov_b32_e32 v38, v4
	v_mov_b32_e32 v39, v4
	v_mov_b32_e32 v40, v4
	v_mov_b32_e32 v41, v4
	v_mov_b32_e32 v42, v4
	v_mov_b32_e32 v43, v4
	v_mov_b32_e32 v52, v4
	v_mov_b32_e32 v53, v4
	v_mov_b32_e32 v54, v4
	v_mov_b32_e32 v55, v4
	v_mov_b32_e32 v56, v4
	v_mov_b32_e32 v57, v4
	v_mov_b32_e32 v58, v4
	v_mov_b32_e32 v59, v4
	v_mov_b32_e32 v68, v4
	v_mov_b32_e32 v69, v4
	v_mov_b32_e32 v70, v4
	v_mov_b32_e32 v71, v4
	v_mov_b32_e32 v72, v4
	v_mov_b32_e32 v73, v4
	v_mov_b32_e32 v74, v4
	v_mov_b32_e32 v75, v4
	v_mov_b32_e32 v12, v4
	v_mov_b32_e32 v13, v4
	v_mov_b32_e32 v14, v4
	v_mov_b32_e32 v15, v4
	v_mov_b32_e32 v16, v4
	v_mov_b32_e32 v17, v4
	v_mov_b32_e32 v18, v4
	v_mov_b32_e32 v19, v4
	v_mov_b32_e32 v44, v4
	v_mov_b32_e32 v45, v4
	v_mov_b32_e32 v46, v4
	v_mov_b32_e32 v47, v4
	v_mov_b32_e32 v48, v4
	v_mov_b32_e32 v49, v4
	v_mov_b32_e32 v50, v4
	v_mov_b32_e32 v51, v4
	v_mov_b32_e32 v60, v4
	v_mov_b32_e32 v61, v4
	v_mov_b32_e32 v62, v4
	v_mov_b32_e32 v63, v4
	v_mov_b32_e32 v64, v4
	v_mov_b32_e32 v65, v4
	v_mov_b32_e32 v66, v4
	v_mov_b32_e32 v67, v4
	v_mov_b32_e32 v76, v4
	v_mov_b32_e32 v77, v4
	v_mov_b32_e32 v78, v4
	v_mov_b32_e32 v79, v4
	v_mov_b32_e32 v80, v4
	v_mov_b32_e32 v81, v4
	v_mov_b32_e32 v82, v4
	v_mov_b32_e32 v83, v4
	v_mov_b32_e32 v84, v4
	v_mov_b32_e32 v85, v4
	v_mov_b32_e32 v86, v4
	v_mov_b32_e32 v87, v4
	v_mov_b32_e32 v88, v4
	v_mov_b32_e32 v89, v4
	v_mov_b32_e32 v90, v4
	v_mov_b32_e32 v91, v4
	v_mov_b32_e32 v100, v4
	v_mov_b32_e32 v101, v4
	v_mov_b32_e32 v102, v4
	v_mov_b32_e32 v103, v4
	v_mov_b32_e32 v104, v4
	v_mov_b32_e32 v105, v4
	v_mov_b32_e32 v106, v4
	v_mov_b32_e32 v107, v4
	v_mov_b32_e32 v116, v4
	v_mov_b32_e32 v117, v4
	v_mov_b32_e32 v118, v4
	v_mov_b32_e32 v119, v4
	v_mov_b32_e32 v120, v4
	v_mov_b32_e32 v121, v4
	v_mov_b32_e32 v122, v4
	v_mov_b32_e32 v123, v4
	v_mov_b32_e32 v132, v4
	v_mov_b32_e32 v133, v4
	v_mov_b32_e32 v134, v4
	v_mov_b32_e32 v135, v4
	v_mov_b32_e32 v136, v4
	v_mov_b32_e32 v137, v4
	v_mov_b32_e32 v138, v4
	v_mov_b32_e32 v139, v4
	v_mov_b32_e32 v92, v4
	v_mov_b32_e32 v93, v4
	v_mov_b32_e32 v94, v4
	v_mov_b32_e32 v95, v4
	v_mov_b32_e32 v96, v4
	v_mov_b32_e32 v97, v4
	v_mov_b32_e32 v98, v4
	v_mov_b32_e32 v99, v4
	v_mov_b32_e32 v108, v4
	v_mov_b32_e32 v109, v4
	v_mov_b32_e32 v110, v4
	v_mov_b32_e32 v111, v4
	v_mov_b32_e32 v112, v4
	v_mov_b32_e32 v113, v4
	v_mov_b32_e32 v114, v4
	v_mov_b32_e32 v115, v4
	v_mov_b32_e32 v124, v4
	v_mov_b32_e32 v125, v4
	v_mov_b32_e32 v126, v4
	v_mov_b32_e32 v127, v4
	v_mov_b32_e32 v128, v4
	v_mov_b32_e32 v129, v4
	v_mov_b32_e32 v130, v4
	v_mov_b32_e32 v131, v4
	v_mov_b32_e32 v140, v4
	v_mov_b32_e32 v141, v4
	v_mov_b32_e32 v142, v4
	v_mov_b32_e32 v143, v4
	v_mov_b32_e32 v144, v4
	v_mov_b32_e32 v145, v4
	v_mov_b32_e32 v146, v4
	v_mov_b32_e32 v147, v4
	s_mov_b64 s[60:61], 0x80
	s_nop 0
.LBB0_439:
	s_add_u32 s30, s28, 0xfffc0080
	s_addc_u32 s31, s29, -1
	s_add_i32 s56, 0, 0x10000
	s_cmp_eq_u32 s55, 12
	s_cselect_b32 s35, s19, s31
	s_cselect_b32 s34, s25, s30
	v_add_u32_e32 v2, s56, v153
	s_cselect_b32 s31, s11, s54
	s_cselect_b32 s30, s27, s53
	s_add_i32 s58, 0, 0x14000
	s_waitcnt vmcnt(0)
	ds_read_b128 v[20:23], v2
	ds_read_b128 v[24:27], v2 offset:1024
	ds_read_b128 v[28:31], v2 offset:2048
	ds_read_b128 v[32:35], v2 offset:3072
	v_add_u32_e32 v2, s58, v153
	ds_read_b128 v[164:167], v2
	ds_read_b128 v[168:171], v2 offset:1024
	ds_read_b128 v[172:175], v2 offset:2048
	ds_read_b128 v[180:183], v2 offset:3072
	v_lshl_add_u64 v[176:177], s[28:29], 0, v[160:161]
	s_add_i32 m0, s42, 0xc000
	ds_read_b128 v[184:187], v178
	ds_read_b128 v[188:191], v178 offset:1024
	ds_read_b128 v[192:195], v178 offset:2048
	ds_read_b128 v[202:205], v178 offset:3072
	ds_read_b128 v[206:209], v178 offset:4096
	ds_read_b128 v[210:213], v178 offset:5120
	ds_read_b128 v[214:217], v178 offset:6144
	ds_read_b128 v[218:221], v178 offset:7168
	global_load_lds_dwordx4 v[176:177], off
	v_lshl_add_u64 v[176:177], s[28:29], 0, v[162:163]
	s_add_i32 m0, s42, 0xe000
	s_nop 0
	global_load_lds_dwordx4 v[176:177], off
	s_waitcnt vmcnt(8)
	s_waitcnt lgkmcnt(0)
	s_barrier
	s_setprio 1
	s_waitcnt lgkmcnt(0)
	v_mfma_f32_16x16x32_bf16 v[144:147], v[20:23], v[184:187], v[144:147]
	v_mfma_f32_16x16x32_bf16 v[140:143], v[28:31], v[184:187], v[140:143]
	v_mfma_f32_16x16x32_bf16 v[128:131], v[20:23], v[192:195], v[128:131]
	v_mfma_f32_16x16x32_bf16 v[124:127], v[28:31], v[192:195], v[124:127]
	v_mfma_f32_16x16x32_bf16 v[112:115], v[20:23], v[206:209], v[112:115]
	v_mfma_f32_16x16x32_bf16 v[108:111], v[28:31], v[206:209], v[108:111]
	v_mfma_f32_16x16x32_bf16 v[96:99], v[20:23], v[214:217], v[96:99]
	v_mfma_f32_16x16x32_bf16 v[92:95], v[28:31], v[214:217], v[92:95]
	v_mfma_f32_16x16x32_bf16 v[144:147], v[24:27], v[188:191], v[144:147]
	v_mfma_f32_16x16x32_bf16 v[140:143], v[32:35], v[188:191], v[140:143]
	v_mfma_f32_16x16x32_bf16 v[128:131], v[24:27], v[202:205], v[128:131]
	v_mfma_f32_16x16x32_bf16 v[124:127], v[32:35], v[202:205], v[124:127]
	v_mfma_f32_16x16x32_bf16 v[112:115], v[24:27], v[210:213], v[112:115]
	v_mfma_f32_16x16x32_bf16 v[108:111], v[32:35], v[210:213], v[108:111]
	v_mfma_f32_16x16x32_bf16 v[96:99], v[24:27], v[218:221], v[96:99]
	v_mfma_f32_16x16x32_bf16 v[92:95], v[32:35], v[218:221], v[92:95]
	s_setprio 0
	s_setprio 1
	v_mfma_f32_16x16x32_bf16 v[136:139], v[164:167], v[184:187], v[136:139]
	v_mfma_f32_16x16x32_bf16 v[132:135], v[172:175], v[184:187], v[132:135]
	v_mfma_f32_16x16x32_bf16 v[120:123], v[164:167], v[192:195], v[120:123]
	v_mfma_f32_16x16x32_bf16 v[116:119], v[172:175], v[192:195], v[116:119]
	v_mfma_f32_16x16x32_bf16 v[104:107], v[164:167], v[206:209], v[104:107]
	v_mfma_f32_16x16x32_bf16 v[100:103], v[172:175], v[206:209], v[100:103]
	v_mfma_f32_16x16x32_bf16 v[88:91], v[164:167], v[214:217], v[88:91]
	v_mfma_f32_16x16x32_bf16 v[84:87], v[172:175], v[214:217], v[84:87]
	v_mfma_f32_16x16x32_bf16 v[136:139], v[168:171], v[188:191], v[136:139]
	v_mfma_f32_16x16x32_bf16 v[132:135], v[180:183], v[188:191], v[132:135]
	v_mfma_f32_16x16x32_bf16 v[120:123], v[168:171], v[202:205], v[120:123]
	v_mfma_f32_16x16x32_bf16 v[116:119], v[180:183], v[202:205], v[116:119]
	v_mfma_f32_16x16x32_bf16 v[104:107], v[168:171], v[210:213], v[104:107]
	v_mfma_f32_16x16x32_bf16 v[100:103], v[180:183], v[210:213], v[100:103]
	v_mfma_f32_16x16x32_bf16 v[88:91], v[168:171], v[218:221], v[88:91]
	v_mfma_f32_16x16x32_bf16 v[84:87], v[180:183], v[218:221], v[84:87]
	s_setprio 0
	s_barrier
	s_add_i32 s56, s56, s41
	v_lshl_add_u64 v[176:177], s[30:31], 0, v[148:149]
	s_mov_b32 m0, s56
	ds_read_b128 v[184:187], v178 offset:16384
	ds_read_b128 v[188:191], v178 offset:17408
	ds_read_b128 v[192:195], v178 offset:18432
	ds_read_b128 v[202:205], v178 offset:19456
	ds_read_b128 v[206:209], v178 offset:20480
	ds_read_b128 v[210:213], v178 offset:21504
	ds_read_b128 v[214:217], v178 offset:22528
	ds_read_b128 v[218:221], v178 offset:23552
	global_load_lds_dwordx4 v[176:177], off
	s_add_i32 m0, s56, 0x2000
	s_add_u32 s56, s30, 0x40000
	v_lshl_add_u64 v[196:197], s[30:31], 0, v[150:151]
	s_addc_u32 s57, s31, 0
	s_add_i32 s58, s58, s41
	global_load_lds_dwordx4 v[196:197], off
	v_lshl_add_u64 v[198:199], s[56:57], 0, v[148:149]
	s_mov_b32 m0, s58
	v_lshl_add_u64 v[222:223], s[34:35], 0, v[150:151]
	global_load_lds_dwordx4 v[198:199], off
	v_lshl_add_u64 v[198:199], s[56:57], 0, v[150:151]
	s_add_i32 m0, s58, 0x2000
	s_nop 0
	global_load_lds_dwordx4 v[198:199], off
	v_lshl_add_u64 v[198:199], s[34:35], 0, v[148:149]
	s_mov_b32 m0, s42
	s_nop 0
	global_load_lds_dwordx4 v[198:199], off
	s_mov_b32 m0, s43
	s_nop 0
	global_load_lds_dwordx4 v[222:223], off
	s_waitcnt vmcnt(8)
	s_waitcnt lgkmcnt(0)
	s_barrier
	s_setprio 1
	s_waitcnt lgkmcnt(0)
	v_mfma_f32_16x16x32_bf16 v[80:83], v[20:23], v[184:187], v[80:83]
	v_mfma_f32_16x16x32_bf16 v[76:79], v[28:31], v[184:187], v[76:79]
	v_mfma_f32_16x16x32_bf16 v[64:67], v[20:23], v[192:195], v[64:67]
	v_mfma_f32_16x16x32_bf16 v[60:63], v[28:31], v[192:195], v[60:63]
	v_mfma_f32_16x16x32_bf16 v[48:51], v[20:23], v[206:209], v[48:51]
	v_mfma_f32_16x16x32_bf16 v[44:47], v[28:31], v[206:209], v[44:47]
	v_mfma_f32_16x16x32_bf16 v[16:19], v[20:23], v[214:217], v[16:19]
	v_mfma_f32_16x16x32_bf16 v[12:15], v[28:31], v[214:217], v[12:15]
	v_mfma_f32_16x16x32_bf16 v[80:83], v[24:27], v[188:191], v[80:83]
	v_mfma_f32_16x16x32_bf16 v[76:79], v[32:35], v[188:191], v[76:79]
	v_mfma_f32_16x16x32_bf16 v[64:67], v[24:27], v[202:205], v[64:67]
	v_mfma_f32_16x16x32_bf16 v[60:63], v[32:35], v[202:205], v[60:63]
	v_mfma_f32_16x16x32_bf16 v[48:51], v[24:27], v[210:213], v[48:51]
	v_mfma_f32_16x16x32_bf16 v[44:47], v[32:35], v[210:213], v[44:47]
	v_mfma_f32_16x16x32_bf16 v[16:19], v[24:27], v[218:221], v[16:19]
	v_mfma_f32_16x16x32_bf16 v[12:15], v[32:35], v[218:221], v[12:15]
	s_setprio 0
	s_setprio 1
	v_mfma_f32_16x16x32_bf16 v[40:43], v[164:167], v[206:209], v[40:43]
	v_mfma_f32_16x16x32_bf16 v[36:39], v[172:175], v[206:209], v[36:39]
	v_mfma_f32_16x16x32_bf16 v[8:11], v[164:167], v[214:217], v[8:11]
	v_mfma_f32_16x16x32_bf16 v[4:7], v[172:175], v[214:217], v[4:7]
	v_mfma_f32_16x16x32_bf16 v[20:23], v[164:167], v[184:187], v[72:75]
	v_mfma_f32_16x16x32_bf16 v[24:27], v[172:175], v[184:187], v[68:71]
	v_mfma_f32_16x16x32_bf16 v[28:31], v[164:167], v[192:195], v[56:59]
	v_mfma_f32_16x16x32_bf16 v[32:35], v[172:175], v[192:195], v[52:55]
	v_mfma_f32_16x16x32_bf16 v[40:43], v[168:171], v[210:213], v[40:43]
	v_mfma_f32_16x16x32_bf16 v[36:39], v[180:183], v[210:213], v[36:39]
	v_mfma_f32_16x16x32_bf16 v[8:11], v[168:171], v[218:221], v[8:11]
	v_mfma_f32_16x16x32_bf16 v[4:7], v[180:183], v[218:221], v[4:7]
	v_mfma_f32_16x16x32_bf16 v[20:23], v[168:171], v[188:191], v[20:23]
	v_mfma_f32_16x16x32_bf16 v[24:27], v[180:183], v[188:191], v[24:27]
	v_mfma_f32_16x16x32_bf16 v[28:31], v[168:171], v[202:205], v[28:31]
	v_mfma_f32_16x16x32_bf16 v[32:35], v[180:183], v[202:205], v[32:35]
	s_setprio 0
	s_barrier
	s_add_i32 s56, 0, 0x18000
	v_add_u32_e32 v2, s56, v153
	s_add_i32 s57, 0, 0x1c000
	ds_read_b128 v[52:55], v2
	ds_read_b128 v[56:59], v2 offset:1024
	ds_read_b128 v[68:71], v2 offset:2048
	ds_read_b128 v[72:75], v2 offset:3072
	v_add_u32_e32 v2, s57, v153
	ds_read_b128 v[164:167], v2
	ds_read_b128 v[168:171], v2 offset:1024
	ds_read_b128 v[172:175], v2 offset:2048
	ds_read_b128 v[180:183], v2 offset:3072
	s_add_u32 s34, s34, 0x40000
	s_addc_u32 s35, s35, 0
	s_mov_b32 m0, s44
	v_lshl_add_u64 v[224:225], s[34:35], 0, v[148:149]
	ds_read_b128 v[184:187], v178 offset:32768
	ds_read_b128 v[188:191], v178 offset:33792
	ds_read_b128 v[192:195], v178 offset:34816
	ds_read_b128 v[202:205], v178 offset:35840
	ds_read_b128 v[206:209], v178 offset:36864
	ds_read_b128 v[210:213], v178 offset:37888
	ds_read_b128 v[214:217], v178 offset:38912
	ds_read_b128 v[218:221], v178 offset:39936
	global_load_lds_dwordx4 v[224:225], off
	v_lshl_add_u64 v[224:225], s[34:35], 0, v[150:151]
	s_mov_b32 m0, s45
	s_nop 0
	global_load_lds_dwordx4 v[224:225], off
	s_waitcnt vmcnt(8)
	s_waitcnt lgkmcnt(0)
	s_barrier
	s_setprio 1
	s_waitcnt lgkmcnt(0)
	v_mfma_f32_16x16x32_bf16 v[144:147], v[52:55], v[184:187], v[144:147]
	v_mfma_f32_16x16x32_bf16 v[140:143], v[68:71], v[184:187], v[140:143]
	v_mfma_f32_16x16x32_bf16 v[128:131], v[52:55], v[192:195], v[128:131]
	v_mfma_f32_16x16x32_bf16 v[124:127], v[68:71], v[192:195], v[124:127]
	v_mfma_f32_16x16x32_bf16 v[112:115], v[52:55], v[206:209], v[112:115]
	v_mfma_f32_16x16x32_bf16 v[108:111], v[68:71], v[206:209], v[108:111]
	v_mfma_f32_16x16x32_bf16 v[96:99], v[52:55], v[214:217], v[96:99]
	v_mfma_f32_16x16x32_bf16 v[92:95], v[68:71], v[214:217], v[92:95]
	v_mfma_f32_16x16x32_bf16 v[144:147], v[56:59], v[188:191], v[144:147]
	v_mfma_f32_16x16x32_bf16 v[140:143], v[72:75], v[188:191], v[140:143]
	v_mfma_f32_16x16x32_bf16 v[128:131], v[56:59], v[202:205], v[128:131]
	v_mfma_f32_16x16x32_bf16 v[124:127], v[72:75], v[202:205], v[124:127]
	v_mfma_f32_16x16x32_bf16 v[112:115], v[56:59], v[210:213], v[112:115]
	v_mfma_f32_16x16x32_bf16 v[108:111], v[72:75], v[210:213], v[108:111]
	v_mfma_f32_16x16x32_bf16 v[96:99], v[56:59], v[218:221], v[96:99]
	v_mfma_f32_16x16x32_bf16 v[92:95], v[72:75], v[218:221], v[92:95]
	s_setprio 0
	s_setprio 1
	v_mfma_f32_16x16x32_bf16 v[136:139], v[164:167], v[184:187], v[136:139]
	v_mfma_f32_16x16x32_bf16 v[132:135], v[172:175], v[184:187], v[132:135]
	v_mfma_f32_16x16x32_bf16 v[120:123], v[164:167], v[192:195], v[120:123]
	v_mfma_f32_16x16x32_bf16 v[116:119], v[172:175], v[192:195], v[116:119]
	v_mfma_f32_16x16x32_bf16 v[104:107], v[164:167], v[206:209], v[104:107]
	v_mfma_f32_16x16x32_bf16 v[100:103], v[172:175], v[206:209], v[100:103]
	v_mfma_f32_16x16x32_bf16 v[88:91], v[164:167], v[214:217], v[88:91]
	v_mfma_f32_16x16x32_bf16 v[84:87], v[172:175], v[214:217], v[84:87]
	v_mfma_f32_16x16x32_bf16 v[136:139], v[168:171], v[188:191], v[136:139]
	v_mfma_f32_16x16x32_bf16 v[132:135], v[180:183], v[188:191], v[132:135]
	v_mfma_f32_16x16x32_bf16 v[120:123], v[168:171], v[202:205], v[120:123]
	v_mfma_f32_16x16x32_bf16 v[116:119], v[180:183], v[202:205], v[116:119]
	v_mfma_f32_16x16x32_bf16 v[104:107], v[168:171], v[210:213], v[104:107]
	v_mfma_f32_16x16x32_bf16 v[100:103], v[180:183], v[210:213], v[100:103]
	v_mfma_f32_16x16x32_bf16 v[88:91], v[168:171], v[218:221], v[88:91]
	v_mfma_f32_16x16x32_bf16 v[84:87], v[180:183], v[218:221], v[84:87]
	s_setprio 0
	s_barrier
	s_add_i32 s34, s56, s41
	v_lshl_add_u64 v[176:177], v[176:177], 0, s[60:61]
	s_mov_b32 m0, s34
	ds_read_b128 v[184:187], v178 offset:49152
	ds_read_b128 v[188:191], v178 offset:50176
	ds_read_b128 v[192:195], v178 offset:51200
	ds_read_b128 v[202:205], v178 offset:52224
	ds_read_b128 v[206:209], v178 offset:53248
	ds_read_b128 v[210:213], v178 offset:54272
	ds_read_b128 v[214:217], v178 offset:55296
	ds_read_b128 v[218:221], v178 offset:56320
	global_load_lds_dwordx4 v[176:177], off
	s_add_i32 m0, s34, 0x2000
	s_add_u32 s30, s30, 0x40080
	v_lshl_add_u64 v[176:177], v[196:197], 0, s[60:61]
	s_addc_u32 s31, s31, 0
	s_add_i32 s34, s57, s41
	global_load_lds_dwordx4 v[176:177], off
	v_lshl_add_u64 v[176:177], s[30:31], 0, v[148:149]
	s_mov_b32 m0, s34
	s_nop 0
	global_load_lds_dwordx4 v[176:177], off
	v_lshl_add_u64 v[176:177], s[30:31], 0, v[150:151]
	s_add_i32 m0, s34, 0x2000
	s_nop 0
	global_load_lds_dwordx4 v[176:177], off
	v_lshl_add_u64 v[176:177], v[198:199], 0, s[60:61]
	s_mov_b32 m0, s47
	s_nop 0
	global_load_lds_dwordx4 v[176:177], off
	v_lshl_add_u64 v[176:177], v[222:223], 0, s[60:61]
	s_mov_b32 m0, s48
	s_nop 0
	global_load_lds_dwordx4 v[176:177], off
	s_waitcnt vmcnt(8)
	s_waitcnt lgkmcnt(0)
	s_barrier
	s_setprio 1
	s_waitcnt lgkmcnt(0)
	v_mfma_f32_16x16x32_bf16 v[80:83], v[52:55], v[184:187], v[80:83]
	v_mfma_f32_16x16x32_bf16 v[76:79], v[68:71], v[184:187], v[76:79]
	v_mfma_f32_16x16x32_bf16 v[64:67], v[52:55], v[192:195], v[64:67]
	v_mfma_f32_16x16x32_bf16 v[60:63], v[68:71], v[192:195], v[60:63]
	v_mfma_f32_16x16x32_bf16 v[48:51], v[52:55], v[206:209], v[48:51]
	v_mfma_f32_16x16x32_bf16 v[44:47], v[68:71], v[206:209], v[44:47]
	v_mfma_f32_16x16x32_bf16 v[16:19], v[52:55], v[214:217], v[16:19]
	v_mfma_f32_16x16x32_bf16 v[12:15], v[68:71], v[214:217], v[12:15]
	v_mfma_f32_16x16x32_bf16 v[80:83], v[56:59], v[188:191], v[80:83]
	v_mfma_f32_16x16x32_bf16 v[76:79], v[72:75], v[188:191], v[76:79]
	v_mfma_f32_16x16x32_bf16 v[64:67], v[56:59], v[202:205], v[64:67]
	v_mfma_f32_16x16x32_bf16 v[60:63], v[72:75], v[202:205], v[60:63]
	v_mfma_f32_16x16x32_bf16 v[48:51], v[56:59], v[210:213], v[48:51]
	v_mfma_f32_16x16x32_bf16 v[44:47], v[72:75], v[210:213], v[44:47]
	v_mfma_f32_16x16x32_bf16 v[16:19], v[56:59], v[218:221], v[16:19]
	v_mfma_f32_16x16x32_bf16 v[12:15], v[72:75], v[218:221], v[12:15]
	s_setprio 0
	s_setprio 1
	v_mfma_f32_16x16x32_bf16 v[20:23], v[164:167], v[184:187], v[20:23]
	v_mfma_f32_16x16x32_bf16 v[72:75], v[168:171], v[188:191], v[20:23]
	v_mfma_f32_16x16x32_bf16 v[20:23], v[172:175], v[184:187], v[24:27]
	v_mfma_f32_16x16x32_bf16 v[68:71], v[180:183], v[188:191], v[20:23]
	v_mfma_f32_16x16x32_bf16 v[20:23], v[164:167], v[192:195], v[28:31]
	v_mfma_f32_16x16x32_bf16 v[56:59], v[168:171], v[202:205], v[20:23]
	v_mfma_f32_16x16x32_bf16 v[20:23], v[172:175], v[192:195], v[32:35]
	v_mfma_f32_16x16x32_bf16 v[52:55], v[180:183], v[202:205], v[20:23]
	v_mfma_f32_16x16x32_bf16 v[20:23], v[164:167], v[206:209], v[40:43]
	v_mfma_f32_16x16x32_bf16 v[40:43], v[168:171], v[210:213], v[20:23]
	v_mfma_f32_16x16x32_bf16 v[20:23], v[172:175], v[206:209], v[36:39]
	v_mfma_f32_16x16x32_bf16 v[8:11], v[164:167], v[214:217], v[8:11]
	v_mfma_f32_16x16x32_bf16 v[4:7], v[172:175], v[214:217], v[4:7]
	v_mfma_f32_16x16x32_bf16 v[36:39], v[180:183], v[210:213], v[20:23]
	v_mfma_f32_16x16x32_bf16 v[8:11], v[168:171], v[218:221], v[8:11]
	v_mfma_f32_16x16x32_bf16 v[4:7], v[180:183], v[218:221], v[4:7]
	s_setprio 0
	s_barrier
	s_add_i32 s55, s55, 2
	s_add_u32 s28, s28, 0x100
	s_addc_u32 s29, s29, 0
	s_add_u32 s53, s53, 0x100
	s_addc_u32 s54, s54, 0
	s_cmp_gt_u32 s55, 13
	s_cbranch_scc0 .LBB0_439
	s_nop 0
	s_and_b64 vcc, exec, s[12:13]
	s_cbranch_vccz .LBB0_442
	s_barrier

.LBB0_1048:
	s_add_u32 s68, s40, 0x100
	s_addc_u32 s69, s41, 0
	s_ashr_i32 s31, s30, 31
	s_lshl_b64 s[36:37], s[30:31], 19
	s_add_u32 s36, s54, s36
	s_addc_u32 s37, s55, s37
	s_and_b64 s[38:39], s[6:7], exec
	s_cselect_b32 s31, s37, s35
	s_cselect_b32 s70, s36, s34
	s_ashr_i32 s29, s28, 31
	s_lshl_b64 s[38:39], s[28:29], 19
	s_add_u32 s38, s14, s38
	s_addc_u32 s39, s15, s39
	s_and_b64 s[42:43], s[6:7], exec
	s_cselect_b32 s29, s39, s41
	s_cselect_b32 s71, s38, s40
	s_add_u32 s40, s34, 0x40080
	s_addc_u32 s41, s35, 0
	v_lshl_add_u64 v[138:139], s[40:41], 0, v[134:135]
	v_lshl_add_u64 v[140:141], s[40:41], 0, v[136:137]
	s_mov_b32 s72, -2
	s_mov_b64 s[40:41], 0
	s_mov_b64 s[76:77], 0x80
	s_nop 0
.LBB0_1049:
	s_add_u32 s42, s34, s40
	s_addc_u32 s43, s35, s41
	s_add_u32 s42, s42, 0x100
	s_addc_u32 s43, s43, 0
	s_add_u32 s73, s68, s40
	s_addc_u32 s74, s69, s41
	s_add_i32 s75, 0, 0x10000
	s_cmpk_eq_i32 s40, 0x700
	s_cselect_b32 s45, s31, s43
	s_cselect_b32 s44, s70, s42
	s_cselect_b32 s43, s29, s74
	s_cselect_b32 s42, s71, s73
	s_add_i32 s73, 0, 0x14000
	v_add_u32_e32 v156, s75, v142
	v_add_u32_e32 v166, s73, v142
	ds_read_b128 v[144:147], v156
	ds_read_b128 v[148:151], v156 offset:1024
	ds_read_b128 v[152:155], v156 offset:2048
	ds_read_b128 v[156:159], v156 offset:3072
	ds_read_b128 v[160:163], v166
	ds_read_b128 v[170:173], v166 offset:1024
	ds_read_b128 v[174:177], v166 offset:2048
	ds_read_b128 v[178:181], v166 offset:3072
	v_lshl_add_u64 v[166:167], v[138:139], 0, s[40:41]
	s_add_i32 m0, s57, 0xc000
	ds_read_b128 v[182:185], v143
	ds_read_b128 v[186:189], v143 offset:1024
	ds_read_b128 v[190:193], v143 offset:2048
	ds_read_b128 v[194:197], v143 offset:3072
	ds_read_b128 v[202:205], v143 offset:4096
	ds_read_b128 v[206:209], v143 offset:5120
	ds_read_b128 v[210:213], v143 offset:6144
	ds_read_b128 v[214:217], v143 offset:7168
	global_load_lds_dwordx4 v[166:167], off
	v_lshl_add_u64 v[166:167], v[140:141], 0, s[40:41]
	s_add_i32 m0, s57, 0xe000
	s_nop 0
	global_load_lds_dwordx4 v[166:167], off
	s_waitcnt vmcnt(8)
	s_waitcnt lgkmcnt(0)
	s_barrier
	s_setprio 1
	s_waitcnt lgkmcnt(0)
	v_mfma_f32_16x16x32_bf16 v[128:131], v[144:147], v[182:185], v[128:131]
	v_mfma_f32_16x16x32_bf16 v[124:127], v[152:155], v[182:185], v[124:127]
	v_mfma_f32_16x16x32_bf16 v[120:123], v[144:147], v[190:193], v[120:123]
	v_mfma_f32_16x16x32_bf16 v[116:119], v[152:155], v[190:193], v[116:119]
	v_mfma_f32_16x16x32_bf16 v[112:115], v[144:147], v[202:205], v[112:115]
	v_mfma_f32_16x16x32_bf16 v[104:107], v[152:155], v[202:205], v[104:107]
	v_mfma_f32_16x16x32_bf16 v[96:99], v[144:147], v[210:213], v[96:99]
	v_mfma_f32_16x16x32_bf16 v[84:87], v[152:155], v[210:213], v[84:87]
	v_mfma_f32_16x16x32_bf16 v[128:131], v[148:151], v[186:189], v[128:131]
	v_mfma_f32_16x16x32_bf16 v[124:127], v[156:159], v[186:189], v[124:127]
	v_mfma_f32_16x16x32_bf16 v[120:123], v[148:151], v[194:197], v[120:123]
	v_mfma_f32_16x16x32_bf16 v[116:119], v[156:159], v[194:197], v[116:119]
	v_mfma_f32_16x16x32_bf16 v[112:115], v[148:151], v[206:209], v[112:115]
	v_mfma_f32_16x16x32_bf16 v[104:107], v[156:159], v[206:209], v[104:107]
	v_mfma_f32_16x16x32_bf16 v[96:99], v[148:151], v[214:217], v[96:99]
	v_mfma_f32_16x16x32_bf16 v[84:87], v[156:159], v[214:217], v[84:87]
	s_setprio 0
	s_setprio 1
	v_mfma_f32_16x16x32_bf16 v[108:111], v[160:163], v[182:185], v[108:111]
	v_mfma_f32_16x16x32_bf16 v[100:103], v[174:177], v[182:185], v[100:103]
	v_mfma_f32_16x16x32_bf16 v[92:95], v[160:163], v[190:193], v[92:95]
	v_mfma_f32_16x16x32_bf16 v[88:91], v[174:177], v[190:193], v[88:91]
	v_mfma_f32_16x16x32_bf16 v[80:83], v[160:163], v[202:205], v[80:83]
	v_mfma_f32_16x16x32_bf16 v[76:79], v[174:177], v[202:205], v[76:79]
	v_mfma_f32_16x16x32_bf16 v[72:75], v[160:163], v[210:213], v[72:75]
	v_mfma_f32_16x16x32_bf16 v[68:71], v[174:177], v[210:213], v[68:71]
	v_mfma_f32_16x16x32_bf16 v[108:111], v[170:173], v[186:189], v[108:111]
	v_mfma_f32_16x16x32_bf16 v[100:103], v[178:181], v[186:189], v[100:103]
	v_mfma_f32_16x16x32_bf16 v[92:95], v[170:173], v[194:197], v[92:95]
	v_mfma_f32_16x16x32_bf16 v[88:91], v[178:181], v[194:197], v[88:91]
	v_mfma_f32_16x16x32_bf16 v[80:83], v[170:173], v[206:209], v[80:83]
	v_mfma_f32_16x16x32_bf16 v[76:79], v[178:181], v[206:209], v[76:79]
	v_mfma_f32_16x16x32_bf16 v[72:75], v[170:173], v[214:217], v[72:75]
	v_mfma_f32_16x16x32_bf16 v[68:71], v[178:181], v[214:217], v[68:71]
	s_setprio 0
	s_barrier
	s_add_i32 s74, s75, s56
	v_lshl_add_u64 v[166:167], s[42:43], 0, v[2:3]
	s_mov_b32 m0, s74
	ds_read_b128 v[182:185], v143 offset:16384
	ds_read_b128 v[186:189], v143 offset:17408
	ds_read_b128 v[190:193], v143 offset:18432
	ds_read_b128 v[194:197], v143 offset:19456
	ds_read_b128 v[202:205], v143 offset:20480
	ds_read_b128 v[206:209], v143 offset:21504
	ds_read_b128 v[210:213], v143 offset:22528
	ds_read_b128 v[214:217], v143 offset:23552
	global_load_lds_dwordx4 v[166:167], off
	s_add_i32 m0, s74, 0x2000
	s_add_u32 s74, s42, 0x40000
	v_lshl_add_u64 v[198:199], s[42:43], 0, v[132:133]
	s_addc_u32 s75, s43, 0
	s_add_i32 s73, s73, s56
	global_load_lds_dwordx4 v[198:199], off
	v_lshl_add_u64 v[218:219], s[74:75], 0, v[2:3]
	s_mov_b32 m0, s73
	v_lshl_add_u64 v[220:221], s[44:45], 0, v[132:133]
	global_load_lds_dwordx4 v[218:219], off
	v_lshl_add_u64 v[218:219], s[74:75], 0, v[132:133]
	s_add_i32 m0, s73, 0x2000
	s_nop 0
	global_load_lds_dwordx4 v[218:219], off
	v_lshl_add_u64 v[218:219], s[44:45], 0, v[2:3]
	s_mov_b32 m0, s57
	s_nop 0
	global_load_lds_dwordx4 v[218:219], off
	s_mov_b32 m0, s59
	s_nop 0
	global_load_lds_dwordx4 v[220:221], off
	s_waitcnt vmcnt(8)
	s_waitcnt lgkmcnt(0)
	s_barrier
	s_setprio 1
	s_waitcnt lgkmcnt(0)
	v_mfma_f32_16x16x32_bf16 v[64:67], v[144:147], v[182:185], v[64:67]
	v_mfma_f32_16x16x32_bf16 v[60:63], v[152:155], v[182:185], v[60:63]
	v_mfma_f32_16x16x32_bf16 v[56:59], v[144:147], v[190:193], v[56:59]
	v_mfma_f32_16x16x32_bf16 v[52:55], v[152:155], v[190:193], v[52:55]
	v_mfma_f32_16x16x32_bf16 v[32:35], v[144:147], v[202:205], v[32:35]
	v_mfma_f32_16x16x32_bf16 v[28:31], v[152:155], v[202:205], v[28:31]
	v_mfma_f32_16x16x32_bf16 v[24:27], v[144:147], v[210:213], v[24:27]
	v_mfma_f32_16x16x32_bf16 v[20:23], v[152:155], v[210:213], v[20:23]
	v_mfma_f32_16x16x32_bf16 v[64:67], v[148:151], v[186:189], v[64:67]
	v_mfma_f32_16x16x32_bf16 v[60:63], v[156:159], v[186:189], v[60:63]
	v_mfma_f32_16x16x32_bf16 v[56:59], v[148:151], v[194:197], v[56:59]
	v_mfma_f32_16x16x32_bf16 v[52:55], v[156:159], v[194:197], v[52:55]
	v_mfma_f32_16x16x32_bf16 v[32:35], v[148:151], v[206:209], v[32:35]
	v_mfma_f32_16x16x32_bf16 v[28:31], v[156:159], v[206:209], v[28:31]
	v_mfma_f32_16x16x32_bf16 v[24:27], v[148:151], v[214:217], v[24:27]
	v_mfma_f32_16x16x32_bf16 v[20:23], v[156:159], v[214:217], v[20:23]
	s_setprio 0
	s_setprio 1
	v_mfma_f32_16x16x32_bf16 v[48:51], v[160:163], v[182:185], v[48:51]
	v_mfma_f32_16x16x32_bf16 v[44:47], v[174:177], v[182:185], v[44:47]
	v_mfma_f32_16x16x32_bf16 v[40:43], v[160:163], v[190:193], v[40:43]
	v_mfma_f32_16x16x32_bf16 v[36:39], v[174:177], v[190:193], v[36:39]
	v_mfma_f32_16x16x32_bf16 v[16:19], v[160:163], v[202:205], v[16:19]
	v_mfma_f32_16x16x32_bf16 v[12:15], v[174:177], v[202:205], v[12:15]
	v_mfma_f32_16x16x32_bf16 v[8:11], v[160:163], v[210:213], v[8:11]
	v_mfma_f32_16x16x32_bf16 v[4:7], v[174:177], v[210:213], v[4:7]
	v_mfma_f32_16x16x32_bf16 v[48:51], v[170:173], v[186:189], v[48:51]
	v_mfma_f32_16x16x32_bf16 v[44:47], v[178:181], v[186:189], v[44:47]
	v_mfma_f32_16x16x32_bf16 v[40:43], v[170:173], v[194:197], v[40:43]
	v_mfma_f32_16x16x32_bf16 v[36:39], v[178:181], v[194:197], v[36:39]
	v_mfma_f32_16x16x32_bf16 v[16:19], v[170:173], v[206:209], v[16:19]
	v_mfma_f32_16x16x32_bf16 v[12:15], v[178:181], v[206:209], v[12:15]
	v_mfma_f32_16x16x32_bf16 v[8:11], v[170:173], v[214:217], v[8:11]
	v_mfma_f32_16x16x32_bf16 v[4:7], v[178:181], v[214:217], v[4:7]
	s_setprio 0
	s_barrier
	s_add_i32 s73, 0, 0x18000
	s_add_i32 s74, 0, 0x1c000
	v_add_u32_e32 v156, s73, v142
	v_add_u32_e32 v169, s74, v142
	ds_read_b128 v[144:147], v156
	ds_read_b128 v[148:151], v156 offset:1024
	ds_read_b128 v[152:155], v156 offset:2048
	ds_read_b128 v[156:159], v156 offset:3072
	ds_read_b128 v[160:163], v169
	ds_read_b128 v[170:173], v169 offset:1024
	ds_read_b128 v[174:177], v169 offset:2048
	ds_read_b128 v[178:181], v169 offset:3072
	s_add_u32 s44, s44, 0x40000
	s_addc_u32 s45, s45, 0
	s_mov_b32 m0, s60
	v_lshl_add_u64 v[222:223], s[44:45], 0, v[2:3]
	ds_read_b128 v[182:185], v143 offset:32768
	ds_read_b128 v[186:189], v143 offset:33792
	ds_read_b128 v[190:193], v143 offset:34816
	ds_read_b128 v[194:197], v143 offset:35840
	ds_read_b128 v[202:205], v143 offset:36864
	ds_read_b128 v[206:209], v143 offset:37888
	ds_read_b128 v[210:213], v143 offset:38912
	ds_read_b128 v[214:217], v143 offset:39936
	global_load_lds_dwordx4 v[222:223], off
	v_lshl_add_u64 v[222:223], s[44:45], 0, v[132:133]
	s_mov_b32 m0, s61
	s_nop 0
	global_load_lds_dwordx4 v[222:223], off
	s_waitcnt vmcnt(8)
	s_waitcnt lgkmcnt(0)
	s_barrier
	s_setprio 1
	s_waitcnt lgkmcnt(0)
	v_mfma_f32_16x16x32_bf16 v[128:131], v[144:147], v[182:185], v[128:131]
	v_mfma_f32_16x16x32_bf16 v[124:127], v[152:155], v[182:185], v[124:127]
	v_mfma_f32_16x16x32_bf16 v[120:123], v[144:147], v[190:193], v[120:123]
	v_mfma_f32_16x16x32_bf16 v[116:119], v[152:155], v[190:193], v[116:119]
	v_mfma_f32_16x16x32_bf16 v[112:115], v[144:147], v[202:205], v[112:115]
	v_mfma_f32_16x16x32_bf16 v[104:107], v[152:155], v[202:205], v[104:107]
	v_mfma_f32_16x16x32_bf16 v[96:99], v[144:147], v[210:213], v[96:99]
	v_mfma_f32_16x16x32_bf16 v[84:87], v[152:155], v[210:213], v[84:87]
	v_mfma_f32_16x16x32_bf16 v[128:131], v[148:151], v[186:189], v[128:131]
	v_mfma_f32_16x16x32_bf16 v[124:127], v[156:159], v[186:189], v[124:127]
	v_mfma_f32_16x16x32_bf16 v[120:123], v[148:151], v[194:197], v[120:123]
	v_mfma_f32_16x16x32_bf16 v[116:119], v[156:159], v[194:197], v[116:119]
	v_mfma_f32_16x16x32_bf16 v[112:115], v[148:151], v[206:209], v[112:115]
	v_mfma_f32_16x16x32_bf16 v[104:107], v[156:159], v[206:209], v[104:107]
	v_mfma_f32_16x16x32_bf16 v[96:99], v[148:151], v[214:217], v[96:99]
	v_mfma_f32_16x16x32_bf16 v[84:87], v[156:159], v[214:217], v[84:87]
	s_setprio 0
	s_setprio 1
	v_mfma_f32_16x16x32_bf16 v[108:111], v[160:163], v[182:185], v[108:111]
	v_mfma_f32_16x16x32_bf16 v[100:103], v[174:177], v[182:185], v[100:103]
	v_mfma_f32_16x16x32_bf16 v[92:95], v[160:163], v[190:193], v[92:95]
	v_mfma_f32_16x16x32_bf16 v[88:91], v[174:177], v[190:193], v[88:91]
	v_mfma_f32_16x16x32_bf16 v[80:83], v[160:163], v[202:205], v[80:83]
	v_mfma_f32_16x16x32_bf16 v[76:79], v[174:177], v[202:205], v[76:79]
	v_mfma_f32_16x16x32_bf16 v[72:75], v[160:163], v[210:213], v[72:75]
	v_mfma_f32_16x16x32_bf16 v[68:71], v[174:177], v[210:213], v[68:71]
	v_mfma_f32_16x16x32_bf16 v[108:111], v[170:173], v[186:189], v[108:111]
	v_mfma_f32_16x16x32_bf16 v[100:103], v[178:181], v[186:189], v[100:103]
	v_mfma_f32_16x16x32_bf16 v[92:95], v[170:173], v[194:197], v[92:95]
	v_mfma_f32_16x16x32_bf16 v[88:91], v[178:181], v[194:197], v[88:91]
	v_mfma_f32_16x16x32_bf16 v[80:83], v[170:173], v[206:209], v[80:83]
	v_mfma_f32_16x16x32_bf16 v[76:79], v[178:181], v[206:209], v[76:79]
	v_mfma_f32_16x16x32_bf16 v[72:75], v[170:173], v[214:217], v[72:75]
	v_mfma_f32_16x16x32_bf16 v[68:71], v[178:181], v[214:217], v[68:71]
	s_setprio 0
	s_barrier
	s_add_i32 s44, s73, s56
	v_lshl_add_u64 v[166:167], v[166:167], 0, s[76:77]
	s_mov_b32 m0, s44
	ds_read_b128 v[182:185], v143 offset:49152
	ds_read_b128 v[186:189], v143 offset:50176
	ds_read_b128 v[190:193], v143 offset:51200
	ds_read_b128 v[194:197], v143 offset:52224
	ds_read_b128 v[202:205], v143 offset:53248
	ds_read_b128 v[206:209], v143 offset:54272
	ds_read_b128 v[210:213], v143 offset:55296
	ds_read_b128 v[214:217], v143 offset:56320
	global_load_lds_dwordx4 v[166:167], off
	s_add_i32 m0, s44, 0x2000
	s_add_u32 s42, s42, 0x40080
	v_lshl_add_u64 v[166:167], v[198:199], 0, s[76:77]
	s_addc_u32 s43, s43, 0
	s_add_i32 s44, s74, s56
	global_load_lds_dwordx4 v[166:167], off
	v_lshl_add_u64 v[166:167], s[42:43], 0, v[2:3]
	s_mov_b32 m0, s44
	s_nop 0
	global_load_lds_dwordx4 v[166:167], off
	v_lshl_add_u64 v[166:167], s[42:43], 0, v[132:133]
	s_add_i32 m0, s44, 0x2000
	s_nop 0
	global_load_lds_dwordx4 v[166:167], off
	v_lshl_add_u64 v[166:167], v[218:219], 0, s[76:77]
	s_mov_b32 m0, s62
	s_nop 0
	global_load_lds_dwordx4 v[166:167], off
	v_lshl_add_u64 v[166:167], v[220:221], 0, s[76:77]
	s_mov_b32 m0, s63
	s_nop 0
	global_load_lds_dwordx4 v[166:167], off
	s_waitcnt vmcnt(8)
	s_waitcnt lgkmcnt(0)
	s_barrier
	s_setprio 1
	s_waitcnt lgkmcnt(0)
	v_mfma_f32_16x16x32_bf16 v[64:67], v[144:147], v[182:185], v[64:67]
	v_mfma_f32_16x16x32_bf16 v[60:63], v[152:155], v[182:185], v[60:63]
	v_mfma_f32_16x16x32_bf16 v[56:59], v[144:147], v[190:193], v[56:59]
	v_mfma_f32_16x16x32_bf16 v[52:55], v[152:155], v[190:193], v[52:55]
	v_mfma_f32_16x16x32_bf16 v[32:35], v[144:147], v[202:205], v[32:35]
	v_mfma_f32_16x16x32_bf16 v[28:31], v[152:155], v[202:205], v[28:31]
	v_mfma_f32_16x16x32_bf16 v[24:27], v[144:147], v[210:213], v[24:27]
	v_mfma_f32_16x16x32_bf16 v[20:23], v[152:155], v[210:213], v[20:23]
	v_mfma_f32_16x16x32_bf16 v[64:67], v[148:151], v[186:189], v[64:67]
	v_mfma_f32_16x16x32_bf16 v[60:63], v[156:159], v[186:189], v[60:63]
	v_mfma_f32_16x16x32_bf16 v[56:59], v[148:151], v[194:197], v[56:59]
	v_mfma_f32_16x16x32_bf16 v[52:55], v[156:159], v[194:197], v[52:55]
	v_mfma_f32_16x16x32_bf16 v[32:35], v[148:151], v[206:209], v[32:35]
	v_mfma_f32_16x16x32_bf16 v[28:31], v[156:159], v[206:209], v[28:31]
	v_mfma_f32_16x16x32_bf16 v[24:27], v[148:151], v[214:217], v[24:27]
	v_mfma_f32_16x16x32_bf16 v[20:23], v[156:159], v[214:217], v[20:23]
	s_setprio 0
	s_setprio 1
	v_mfma_f32_16x16x32_bf16 v[48:51], v[160:163], v[182:185], v[48:51]
	v_mfma_f32_16x16x32_bf16 v[44:47], v[174:177], v[182:185], v[44:47]
	v_mfma_f32_16x16x32_bf16 v[40:43], v[160:163], v[190:193], v[40:43]
	v_mfma_f32_16x16x32_bf16 v[36:39], v[174:177], v[190:193], v[36:39]
	v_mfma_f32_16x16x32_bf16 v[16:19], v[160:163], v[202:205], v[16:19]
	v_mfma_f32_16x16x32_bf16 v[12:15], v[174:177], v[202:205], v[12:15]
	v_mfma_f32_16x16x32_bf16 v[8:11], v[160:163], v[210:213], v[8:11]
	v_mfma_f32_16x16x32_bf16 v[4:7], v[174:177], v[210:213], v[4:7]
	v_mfma_f32_16x16x32_bf16 v[48:51], v[170:173], v[186:189], v[48:51]
	v_mfma_f32_16x16x32_bf16 v[44:47], v[178:181], v[186:189], v[44:47]
	v_mfma_f32_16x16x32_bf16 v[40:43], v[170:173], v[194:197], v[40:43]
	v_mfma_f32_16x16x32_bf16 v[36:39], v[178:181], v[194:197], v[36:39]
	v_mfma_f32_16x16x32_bf16 v[16:19], v[170:173], v[206:209], v[16:19]
	v_mfma_f32_16x16x32_bf16 v[12:15], v[178:181], v[206:209], v[12:15]
	v_mfma_f32_16x16x32_bf16 v[8:11], v[170:173], v[214:217], v[8:11]
	v_mfma_f32_16x16x32_bf16 v[4:7], v[178:181], v[214:217], v[4:7]
	s_setprio 0
	s_barrier
	s_add_i32 s72, s72, 2
	s_add_u32 s40, s40, 0x100
	s_addc_u32 s41, s41, 0
	s_cmp_gt_u32 s72, 13
	s_cbranch_scc0 .LBB0_1049
	s_nop 0
	s_and_b64 vcc, exec, s[26:27]
	s_cbranch_vccz .LBB0_1052
	s_barrier
